# cross-lane reductions of the sample-chain step and of the decode-attention softmax by DPP / permlane-swap adds instead of dependent ds_bpermute round trips (18 LDS crossbar trips removed per item)
# baseline (speedup 1.0000x reference)
.LBB0_2679:
	s_or_b64 exec, exec, s[22:23]
	s_waitcnt lgkmcnt(0)
	s_barrier
	s_and_saveexec_b64 s[22:23], s[8:9]
	s_cbranch_execz .LBB0_2684
	v_lshl_add_u32 v12, s34, 2, v41
	v_ashrrev_i32_e32 v13, 31, v12
	v_lshl_add_u64 v[12:13], v[12:13], 2, s[80:81]
	global_load_dword v14, v[12:13], off
	ds_read2st64_b32 v[12:13], v25 offset0:4 offset1:5
	v_mov_b32_e32 v15, 0xff800000
	s_and_saveexec_b64 s[24:25], s[12:13]
	ds_read_b32 v15, v24 offset:1536
	s_or_b64 exec, exec, s[24:25]
	s_waitcnt vmcnt(0)
	v_max_f32_e32 v16, v14, v14
	s_waitcnt lgkmcnt(0)
	v_max_f32_e32 v17, v15, v15
	v_max_f32_e32 v16, v17, v16
	v_max3_f32 v16, v12, v13, v16
	s_nop 1
	v_max_f32_dpp v16, v16, v16 quad_perm:[1,0,3,2] row_mask:0xf bank_mask:0xf bound_ctrl:1
	s_nop 1
	v_max_f32_dpp v16, v16, v16 quad_perm:[2,3,0,1] row_mask:0xf bank_mask:0xf bound_ctrl:1
	s_nop 1
	v_max_f32_dpp v16, v16, v16 row_ror:4 row_mask:0xf bank_mask:0xf bound_ctrl:1
	s_nop 1
	v_max_f32_dpp v16, v16, v16 row_ror:8 row_mask:0xf bank_mask:0xf bound_ctrl:1
	s_nop 1
	v_mov_b32_e32 v19, v16
	s_nop 1
	v_permlane16_swap_b32_e32 v19, v16
	v_max_f32_e32 v16, v16, v19
	v_mov_b32_e32 v19, v16
	s_nop 1
	v_permlane32_swap_b32_e32 v19, v16
	v_max_f32_e32 v16, v16, v19
	v_sub_f32_e32 v12, v12, v16
	v_mul_f32_e32 v12, 0x3fb8aa3b, v12
	v_exp_f32_e32 v35, v12
	v_sub_f32_e32 v12, v13, v16
	v_mul_f32_e32 v13, 0x3fb8aa3b, v12
	v_sub_f32_e32 v12, v15, v16
	v_mul_f32_e32 v12, 0x3fb8aa3b, v12
	v_exp_f32_e32 v12, v12
	v_exp_f32_e32 v15, v13
	v_sub_f32_e32 v14, v14, v16
	v_mul_f32_e32 v14, 0x3fb8aa3b, v14
	v_cndmask_b32_e64 v13, 0, v12, s[12:13]
	v_add_f32_e32 v36, v35, v15
	v_add_f32_e32 v13, v36, v13
	v_exp_f32_e32 v14, v14
	s_nop 1
	v_add_f32_dpp v13, v13, v13 quad_perm:[1,0,3,2] row_mask:0xf bank_mask:0xf bound_ctrl:1
	s_nop 1
	v_add_f32_dpp v13, v13, v13 quad_perm:[2,3,0,1] row_mask:0xf bank_mask:0xf bound_ctrl:1
	s_nop 1
	v_add_f32_dpp v13, v13, v13 row_ror:4 row_mask:0xf bank_mask:0xf bound_ctrl:1
	s_nop 1
	v_add_f32_dpp v13, v13, v13 row_ror:8 row_mask:0xf bank_mask:0xf bound_ctrl:1
	s_nop 1
	v_mov_b32_e32 v18, v13
	s_nop 1
	v_permlane16_swap_b32_e32 v18, v13
	v_add_f32_e32 v13, v13, v18
	v_mov_b32_e32 v18, v13
	s_nop 1
	v_permlane32_swap_b32_e32 v18, v13
	v_add_f32_e32 v13, v13, v18
	v_add_f32_e32 v13, v14, v13
	v_div_scale_f32 v14, s[24:25], v13, v13, 1.0
	v_rcp_f32_e32 v16, v14
	v_div_scale_f32 v17, vcc, 1.0, v13, 1.0
	v_fma_f32 v18, -v14, v16, 1.0
	v_fmac_f32_e32 v16, v18, v16
	v_mul_f32_e32 v18, v17, v16
	v_fma_f32 v19, -v14, v18, v17
	v_fmac_f32_e32 v18, v19, v16
	v_fma_f32 v14, -v14, v18, v17
	v_div_fmas_f32 v14, v14, v16, v18
	v_div_fixup_f32 v13, v14, v13, 1.0
	v_mul_f32_e32 v14, v35, v13
	v_mul_f32_e32 v15, v15, v13
	ds_write2st64_b32 v25, v14, v15 offset0:4 offset1:5
	s_and_b64 exec, exec, s[12:13]
	v_mul_f32_e32 v12, v12, v13
	ds_write_b32 v24, v12 offset:1536
